# S5 prompt output part: feed-through operands prefetched at tile top, counted wait
# speedup vs baseline: 1.0875x; 1.0091x over previous
; #define LAS __attribute__((address_space(3)))
; DI unsigned f2bf(float f) { unsigned u = __float_as_uint(f); return (u + 0x7fffu + ((u >> 16) & 1u)) >> 16; }
; #define MFMA16(a, b, c) __builtin_amdgcn_mfma_f32_16x16x32_bf16((a), (b), (c), 0, 0, 0)
; template <bool OUT>
; DI void s5_tile(const S5C& K, const float* U, int row0, int g, int nruns, int nvalid, float (&hre)[2], float (&him)[2], LAS bf16_t* Hs, const float* dvec, bf16_t* YC0, int lane) {
;     ...
;         for (int i = 0; i < 16; ++i) { const int tr = (i & 3) + 8 * (i >> 2) + 4 * half; LAS bf16_t* hp = Hs + tr * 136 + tok;
; #pragma unroll
;             for (int st = 0; st < 2; ++st) { hp[st * 32] = (bf16_t)f2bf(dre[st][i]); hp[64 + st * 32] = (bf16_t)f2bf(dim[st][i]); } }
;         const int l15 = lane & 15, quad = lane >> 4;
; #pragma unroll
;         for (int tt = 0; tt < 2; ++tt) {
;             if (tt * 16 < nvalid) {
;                 f32x4 acc = {0.f, 0.f, 0.f, 0.f};
; #pragma unroll
;                 for (int ks = 0; ks < 4; ++ks) { const bf16x8 hf8 = *(const LAS bf16x8*)(Hs + (tt * 16 + l15) * 136 + ks * 32 + quad * 8); acc = MFMA16(K.cf[ks], hf8, acc); }
.LBB0_933:
	s_or_b64 exec, exec, s[14:15]
	s_waitcnt lgkmcnt(0)
	v_bfe_u32 v33, v0, 16, 1
	v_add3_u32 v0, v0, v33, s94
	ds_write_b16_d16_hi v173, v0
	v_bfe_u32 v0, v80, 16, 1
	v_add3_u32 v0, v80, v0, s94
	ds_write_b16_d16_hi v173, v0 offset:128
	v_bfe_u32 v0, v16, 16, 1
	v_add3_u32 v0, v16, v0, s94
	ds_write_b16_d16_hi v173, v0 offset:64
	v_bfe_u32 v0, v64, 16, 1
	v_add3_u32 v0, v64, v0, s94
	ds_write_b16_d16_hi v173, v0 offset:192
	v_bfe_u32 v0, v1, 16, 1
	v_add3_u32 v0, v1, v0, s94
	ds_write_b16_d16_hi v173, v0 offset:272
	v_bfe_u32 v0, v81, 16, 1
	v_add3_u32 v0, v81, v0, s94
	ds_write_b16_d16_hi v173, v0 offset:400
	v_bfe_u32 v0, v17, 16, 1
	v_add3_u32 v0, v17, v0, s94
	ds_write_b16_d16_hi v173, v0 offset:336
	v_bfe_u32 v0, v65, 16, 1
	v_add3_u32 v0, v65, v0, s94
	ds_write_b16_d16_hi v173, v0 offset:464
	v_bfe_u32 v0, v2, 16, 1
	v_add3_u32 v0, v2, v0, s94
	ds_write_b16_d16_hi v173, v0 offset:544
	v_bfe_u32 v0, v82, 16, 1
	v_add3_u32 v0, v82, v0, s94
	ds_write_b16_d16_hi v173, v0 offset:672
	v_bfe_u32 v0, v18, 16, 1
	v_add3_u32 v0, v18, v0, s94
	ds_write_b16_d16_hi v173, v0 offset:608
	v_bfe_u32 v0, v66, 16, 1
	v_add3_u32 v0, v66, v0, s94
	ds_write_b16_d16_hi v173, v0 offset:736
	v_bfe_u32 v0, v3, 16, 1
	v_add3_u32 v0, v3, v0, s94
	ds_write_b16_d16_hi v173, v0 offset:816
	v_bfe_u32 v0, v83, 16, 1
	v_add3_u32 v0, v83, v0, s94
	ds_write_b16_d16_hi v173, v0 offset:944
	v_bfe_u32 v0, v19, 16, 1
	v_add3_u32 v0, v19, v0, s94
	ds_write_b16_d16_hi v173, v0 offset:880
	v_bfe_u32 v0, v67, 16, 1
	v_add3_u32 v0, v67, v0, s94
	ds_write_b16_d16_hi v173, v0 offset:1008
	v_bfe_u32 v0, v4, 16, 1
	v_add3_u32 v0, v4, v0, s94
	ds_write_b16_d16_hi v173, v0 offset:2176
	v_bfe_u32 v0, v84, 16, 1
	v_add3_u32 v0, v84, v0, s94
	ds_write_b16_d16_hi v173, v0 offset:2304
	v_bfe_u32 v0, v20, 16, 1
	v_add3_u32 v0, v20, v0, s94
	ds_write_b16_d16_hi v173, v0 offset:2240
	v_bfe_u32 v0, v68, 16, 1
	v_add3_u32 v0, v68, v0, s94
	ds_write_b16_d16_hi v173, v0 offset:2368
	v_bfe_u32 v0, v5, 16, 1
	v_add3_u32 v0, v5, v0, s94
	ds_write_b16_d16_hi v173, v0 offset:2448
	v_bfe_u32 v0, v85, 16, 1
	v_add3_u32 v0, v85, v0, s94
	ds_write_b16_d16_hi v173, v0 offset:2576
	v_bfe_u32 v0, v21, 16, 1
	v_add3_u32 v0, v21, v0, s94
	ds_write_b16_d16_hi v173, v0 offset:2512
	v_bfe_u32 v0, v69, 16, 1
	v_add3_u32 v0, v69, v0, s94
	ds_write_b16_d16_hi v173, v0 offset:2640
	v_bfe_u32 v0, v6, 16, 1
	v_add3_u32 v0, v6, v0, s94
	ds_write_b16_d16_hi v173, v0 offset:2720
	v_bfe_u32 v0, v86, 16, 1
	v_add3_u32 v0, v86, v0, s94
	ds_write_b16_d16_hi v173, v0 offset:2848
	v_bfe_u32 v0, v22, 16, 1
	v_add3_u32 v0, v22, v0, s94
	ds_write_b16_d16_hi v173, v0 offset:2784
	v_bfe_u32 v0, v70, 16, 1
	v_add3_u32 v0, v70, v0, s94
	ds_write_b16_d16_hi v173, v0 offset:2912
	v_bfe_u32 v0, v7, 16, 1
	v_add3_u32 v0, v7, v0, s94
	ds_write_b16_d16_hi v173, v0 offset:2992
	v_bfe_u32 v0, v87, 16, 1
	v_add3_u32 v0, v87, v0, s94
	ds_write_b16_d16_hi v173, v0 offset:3120
	v_bfe_u32 v0, v23, 16, 1
	v_add3_u32 v0, v23, v0, s94
	ds_write_b16_d16_hi v173, v0 offset:3056
	v_bfe_u32 v0, v71, 16, 1
	v_add3_u32 v0, v71, v0, s94
	ds_write_b16_d16_hi v173, v0 offset:3184
	v_bfe_u32 v0, v8, 16, 1
	v_add3_u32 v0, v8, v0, s94
	ds_write_b16_d16_hi v173, v0 offset:4352
	v_bfe_u32 v0, v88, 16, 1
	v_add3_u32 v0, v88, v0, s94
	ds_write_b16_d16_hi v173, v0 offset:4480
	v_bfe_u32 v0, v24, 16, 1
	v_add3_u32 v0, v24, v0, s94
	ds_write_b16_d16_hi v173, v0 offset:4416
	v_bfe_u32 v0, v72, 16, 1
	v_add3_u32 v0, v72, v0, s94
	ds_write_b16_d16_hi v173, v0 offset:4544
	v_bfe_u32 v0, v9, 16, 1
	v_add3_u32 v0, v9, v0, s94
	ds_write_b16_d16_hi v173, v0 offset:4624
	v_bfe_u32 v0, v89, 16, 1
	v_add3_u32 v0, v89, v0, s94
	ds_write_b16_d16_hi v173, v0 offset:4752
	v_bfe_u32 v0, v25, 16, 1
	v_add3_u32 v0, v25, v0, s94
	ds_write_b16_d16_hi v173, v0 offset:4688
	v_bfe_u32 v0, v73, 16, 1
	v_add3_u32 v0, v73, v0, s94
	ds_write_b16_d16_hi v173, v0 offset:4816
	v_bfe_u32 v0, v10, 16, 1
	v_add3_u32 v0, v10, v0, s94
	ds_write_b16_d16_hi v173, v0 offset:4896
	v_bfe_u32 v0, v90, 16, 1
	v_add3_u32 v0, v90, v0, s94
	ds_write_b16_d16_hi v173, v0 offset:5024
	v_bfe_u32 v0, v26, 16, 1
	v_add3_u32 v0, v26, v0, s94
	ds_write_b16_d16_hi v173, v0 offset:4960
	v_bfe_u32 v0, v74, 16, 1
	v_add3_u32 v0, v74, v0, s94
	ds_write_b16_d16_hi v173, v0 offset:5088
	v_bfe_u32 v0, v11, 16, 1
	v_add3_u32 v0, v11, v0, s94
	ds_write_b16_d16_hi v173, v0 offset:5168
	v_bfe_u32 v0, v91, 16, 1
	v_add3_u32 v0, v91, v0, s94
	ds_write_b16_d16_hi v173, v0 offset:5296
	v_bfe_u32 v0, v27, 16, 1
	v_add3_u32 v0, v27, v0, s94
	ds_write_b16_d16_hi v173, v0 offset:5232
	v_bfe_u32 v0, v75, 16, 1
	v_add3_u32 v0, v75, v0, s94
	ds_write_b16_d16_hi v173, v0 offset:5360
	v_bfe_u32 v0, v12, 16, 1
	v_add3_u32 v0, v12, v0, s94
	ds_write_b16_d16_hi v173, v0 offset:6528
	v_bfe_u32 v0, v92, 16, 1
	v_add3_u32 v0, v92, v0, s94
	ds_write_b16_d16_hi v173, v0 offset:6656
	v_bfe_u32 v0, v28, 16, 1
	v_add3_u32 v0, v28, v0, s94
	ds_write_b16_d16_hi v173, v0 offset:6592
	v_bfe_u32 v0, v76, 16, 1
	v_add3_u32 v0, v76, v0, s94
	ds_write_b16_d16_hi v173, v0 offset:6720
	v_bfe_u32 v0, v13, 16, 1
	v_add3_u32 v0, v13, v0, s94
	ds_write_b16_d16_hi v173, v0 offset:6800
	v_bfe_u32 v0, v93, 16, 1
	v_add3_u32 v0, v93, v0, s94
	ds_write_b16_d16_hi v173, v0 offset:6928
	v_bfe_u32 v0, v29, 16, 1
	v_add3_u32 v0, v29, v0, s94
	ds_write_b16_d16_hi v173, v0 offset:6864
	v_bfe_u32 v0, v77, 16, 1
	v_add3_u32 v0, v77, v0, s94
	ds_write_b16_d16_hi v173, v0 offset:6992
	v_bfe_u32 v0, v14, 16, 1
	v_add3_u32 v0, v14, v0, s94
	ds_write_b16_d16_hi v173, v0 offset:7072
	v_bfe_u32 v0, v94, 16, 1
	v_add3_u32 v0, v94, v0, s94
	ds_write_b16_d16_hi v173, v0 offset:7200
	v_bfe_u32 v0, v30, 16, 1
	v_add3_u32 v0, v30, v0, s94
	ds_write_b16_d16_hi v173, v0 offset:7136
	v_bfe_u32 v0, v78, 16, 1
	v_add3_u32 v0, v78, v0, s94
	ds_write_b16_d16_hi v173, v0 offset:7264
	v_bfe_u32 v0, v15, 16, 1
	v_add3_u32 v0, v15, v0, s94
	ds_write_b16_d16_hi v173, v0 offset:7344
	v_bfe_u32 v0, v95, 16, 1
	v_add3_u32 v0, v95, v0, s94
	ds_write_b16_d16_hi v173, v0 offset:7472
	v_bfe_u32 v0, v31, 16, 1
	v_add3_u32 v0, v31, v0, s94
	ds_write_b16_d16_hi v173, v0 offset:7408
	v_bfe_u32 v0, v79, 16, 1
	v_add3_u32 v0, v79, v0, s94
	ds_write_b16_d16_hi v173, v0 offset:7536
	v_add_u32_e32 v22, v174, v176
	ds_read_b128 v[0:3], v22
	ds_read_b128 v[4:7], v22 offset:64
	s_waitcnt lgkmcnt(1)
; __device__ __forceinline__ void st_bf4(bf16_t* p, const f32x4 v) { u32x2 w; w.x = cvt_pk_bf16(v[0], v[1]); w.y = cvt_pk_bf16(v[2], v[3]); *(u32x2*)p = w; }
; #define LAS __attribute__((address_space(3)))
; #define MFMA16(a, b, c) __builtin_amdgcn_mfma_f32_16x16x32_bf16((a), (b), (c), 0, 0, 0)
; DI float gelu_tanh(float y) { const float z = 1.5957691216057308f * (y + 0.044715f * y * y * y); return y * sigm(z); }
; template <bool OUT>
; DI void s5_tile(const S5C& K, const float* U, int row0, int g, int nruns, int nvalid, float (&hre)[2], float (&him)[2], LAS bf16_t* Hs, const float* dvec, bf16_t* YC0, int lane) {
;     ...
;             if (tt * 16 < nvalid) {
;                 f32x4 acc = {0.f, 0.f, 0.f, 0.f};
; #pragma unroll
;                 for (int ks = 0; ks < 4; ++ks) { const bf16x8 hf8 = *(const LAS bf16x8*)(Hs + (tt * 16 + l15) * 136 + ks * 32 + quad * 8); acc = MFMA16(K.cf[ks], hf8, acc); }
;                 const int tk = tt * 16 + l15;
;                 if (tk < nvalid) { const size_t ro = (size_t)(row0 + tk) * 512 + g * 16 + quad * 4;
;                     const f32x4 u4 = *(const f32x4*)(U + ro), d4 = *(const f32x4*)(dvec + quad * 4); f32x4 y = acc + d4 * u4;
;                     y[0] = gelu_tanh(y[0]); y[1] = gelu_tanh(y[1]); y[2] = gelu_tanh(y[2]); y[3] = gelu_tanh(y[3]);
;                     st_bf4(YC0 + ro, y); }
	v_mfma_f32_16x16x32_bf16 v[0:3], v[102:105], v[0:3], 0
	v_add_u32_e32 v16, s30, v180
	v_ashrrev_i32_e32 v17, 31, v16
	v_lshlrev_b64 v[18:19], 9, v[16:17]
	s_waitcnt lgkmcnt(0)
	v_mfma_f32_16x16x32_bf16 v[0:3], v[110:113], v[4:7], v[0:3]
	ds_read_b128 v[4:7], v22 offset:128
	ds_read_b128 v[8:11], v22 offset:192
	v_or_b32_e32 v18, v18, v96
	ds_bpermute_b32 v23, v143, v34
	s_waitcnt lgkmcnt(2)
	v_mfma_f32_16x16x32_bf16 v[0:3], v[118:121], v[4:7], v[0:3]
	ds_bpermute_b32 v24, v143, v32
	s_waitcnt lgkmcnt(2)
	v_mfma_f32_16x16x32_bf16 v[0:3], v[126:129], v[8:11], v[0:3]
	ds_bpermute_b32 v25, v143, v163
	ds_bpermute_b32 v26, v143, v165
	s_add_i32 s30, s30, 32
	s_waitcnt lgkmcnt(2)
	v_cndmask_b32_e64 v162, v162, v24, s[6:7]
	v_cndmask_b32_e64 v164, v164, v23, s[6:7]
	s_waitcnt lgkmcnt(1)
	v_cndmask_b32_e64 v163, v163, v25, s[6:7]
	s_waitcnt lgkmcnt(0)
	v_cndmask_b32_e64 v165, v165, v26, s[6:7]
	s_cmpk_eq_i32 s30, 0x100
	s_waitcnt vmcnt(0)
	v_pk_fma_f32 v[0:1], v[214:215], v[222:223], v[0:1]
	v_pk_fma_f32 v[2:3], v[216:217], v[224:225], v[2:3]
	v_mul_f32_e32 v4, 0x3d372713, v0
	v_mul_f32_e32 v5, 0x3d372713, v1
	v_mul_f32_e32 v7, 0x3d372713, v3
	v_mul_f32_e32 v4, v0, v4
	v_mul_f32_e32 v5, v1, v5
	v_mul_f32_e32 v6, 0x3d372713, v2
	v_mul_f32_e32 v7, v3, v7
	v_fma_f32 v4, v0, v4, v0
	v_fma_f32 v5, v1, v5, v1
	v_mul_f32_e32 v6, v2, v6
	v_fma_f32 v7, v3, v7, v3
	v_mul_f32_e32 v4, 0x3fcc422a, v4
	v_mul_f32_e32 v5, 0x3fcc422a, v5
	v_fma_f32 v6, v2, v6, v2
	v_mul_f32_e32 v7, 0x3fcc422a, v7
	v_mul_f32_e32 v4, 0xbfb8aa3b, v4
	v_mul_f32_e32 v5, 0xbfb8aa3b, v5
	v_mul_f32_e32 v6, 0x3fcc422a, v6
	v_mul_f32_e32 v7, 0xbfb8aa3b, v7
	v_exp_f32_e32 v4, v4
	v_exp_f32_e32 v5, v5
	v_mul_f32_e32 v6, 0xbfb8aa3b, v6
	v_exp_f32_e32 v7, v7
	v_exp_f32_e32 v6, v6
	v_add_f32_e32 v4, 1.0, v4
	v_add_f32_e32 v5, 1.0, v5
	v_add_f32_e32 v7, 1.0, v7
	v_rcp_f32_e32 v4, v4
	v_rcp_f32_e32 v5, v5
	v_add_f32_e32 v6, 1.0, v6
	v_rcp_f32_e32 v7, v7
	v_rcp_f32_e32 v6, v6
	v_mul_f32_e32 v4, v0, v4
	v_mul_f32_e32 v5, v1, v5
	v_mul_f32_e32 v3, v3, v7
	v_lshl_add_u64 v[0:1], v[18:19], 1, s[16:17]
	v_mul_f32_e32 v6, v2, v6
	v_cvt_pk_bf16_f32 v2, v4, v5
	v_cvt_pk_bf16_f32 v3, v6, v3
	global_store_dwordx2 v[0:1], v[2:3], off
	v_add_u32_e32 v0, 16, v16
	v_ashrrev_i32_e32 v1, 31, v0
	v_lshlrev_b64 v[20:21], 9, v[0:1]
	v_or_b32_e32 v20, v20, v96
	ds_read_b128 v[8:11], v22 offset:4352
	ds_read_b128 v[12:15], v22 offset:4416
	s_waitcnt lgkmcnt(1)
	v_mfma_f32_16x16x32_bf16 v[8:11], v[102:105], v[8:11], 0
	ds_read_b128 v[16:19], v22 offset:4480
	s_waitcnt lgkmcnt(1)
	v_mfma_f32_16x16x32_bf16 v[8:11], v[110:113], v[12:15], v[8:11]
	ds_read_b128 v[12:15], v22 offset:4544
	s_waitcnt lgkmcnt(1)
	v_mfma_f32_16x16x32_bf16 v[8:11], v[118:121], v[16:19], v[8:11]
	s_waitcnt lgkmcnt(0)
	v_mfma_f32_16x16x32_bf16 v[8:11], v[126:129], v[12:15], v[8:11]
	s_waitcnt vmcnt(1)
	s_nop 6
	v_pk_fma_f32 v[0:1], v[218:219], v[222:223], v[8:9]
	v_pk_fma_f32 v[2:3], v[220:221], v[224:225], v[10:11]
	v_mul_f32_e32 v4, 0x3d372713, v0
	v_mul_f32_e32 v5, 0x3d372713, v1
	v_mul_f32_e32 v7, 0x3d372713, v3
	v_mul_f32_e32 v4, v0, v4
	v_mul_f32_e32 v5, v1, v5
	v_mul_f32_e32 v6, 0x3d372713, v2
	v_mul_f32_e32 v7, v3, v7
	v_fma_f32 v4, v0, v4, v0
	v_fma_f32 v5, v1, v5, v1
	v_mul_f32_e32 v6, v2, v6
	v_fma_f32 v7, v3, v7, v3
	v_mul_f32_e32 v4, 0x3fcc422a, v4
	v_mul_f32_e32 v5, 0x3fcc422a, v5
	v_fma_f32 v6, v2, v6, v2
	v_mul_f32_e32 v7, 0x3fcc422a, v7
	v_mul_f32_e32 v4, 0xbfb8aa3b, v4
	v_mul_f32_e32 v5, 0xbfb8aa3b, v5
	v_mul_f32_e32 v6, 0x3fcc422a, v6
	v_mul_f32_e32 v7, 0xbfb8aa3b, v7
	v_exp_f32_e32 v4, v4
	v_exp_f32_e32 v5, v5
	v_mul_f32_e32 v6, 0xbfb8aa3b, v6
	v_exp_f32_e32 v7, v7
	v_exp_f32_e32 v6, v6
	v_add_f32_e32 v4, 1.0, v4
	v_add_f32_e32 v5, 1.0, v5
	v_add_f32_e32 v7, 1.0, v7
	v_rcp_f32_e32 v4, v4
	v_rcp_f32_e32 v5, v5
	v_add_f32_e32 v6, 1.0, v6
	v_rcp_f32_e32 v7, v7
	v_rcp_f32_e32 v6, v6
	v_mul_f32_e32 v4, v0, v4
	v_mul_f32_e32 v5, v1, v5
	v_mul_f32_e32 v3, v3, v7
	v_lshl_add_u64 v[0:1], v[20:21], 1, s[16:17]
	v_mul_f32_e32 v6, v2, v6
	v_cvt_pk_bf16_f32 v2, v4, v5
	v_cvt_pk_bf16_f32 v3, v6, v3
	global_store_dwordx2 v[0:1], v[2:3], off
	s_cbranch_scc1 .LBB0_952
; DI bf16x8 pack8(const f32x4 a, const f32x4 b) { u32x4 p; p.x = cvt_pk_bf16(a[0], a[1]); p.y = cvt_pk_bf16(a[2], a[3]); p.z = cvt_pk_bf16(b[0], b[1]); p.w = cvt_pk_bf16(b[2], b[3]); return __builtin_bit_cast(bf16x8, p); }
; #define MFMA32(a, b, c) __builtin_amdgcn_mfma_f32_32x32x16_bf16((a), (b), (c), 0, 0, 0)
; template <bool OUT>
; DI void s5_tile(const S5C& K, const float* U, int row0, int g, int nruns, int nvalid, float (&hre)[2], float (&him)[2], LAS bf16_t* Hs, const float* dvec, bf16_t* YC0, int lane) {
;     ...
;     if (tok < nvalid) { const float* up = U + (size_t)(row0 + tok) * 512 + g * 16 + half * 8; af = pack8(*(const f32x4*)up, *(const f32x4*)(up + 4)); }
;     f32x16 z16;
; #pragma unroll
;     for (int i = 0; i < 16; ++i) z16[i] = 0.f;
;     f32x16 dre[2], dim[2];
; #pragma unroll
;     for (int st = 0; st < 2; ++st) { dre[st] = MFMA32(af, K.bbf[st], z16); dim[st] = MFMA32(af, K.bbf[2 + st], z16); }
; #pragma unroll
;     for (int r = 0; r < 8; ++r) {
;         if (r < nruns) {
;             const int hf = r & 1, i0 = 4 * (r >> 1);
;             if (half == hf) {
; #pragma unroll
;                 for (int k = 0; k < 4; ++k)
; #pragma unroll
;                     for (int st = 0; st < 2; ++st) { const float nr = K.are[st] * hre[st] - K.aim[st] * him[st] + dre[st][i0 + k]; const float ni = K.are[st] * him[st] + K.aim[st] * hre[st] + dim[st][i0 + k];
;                         hre[st] = nr; him[st] = ni; dre[st][i0 + k] = nr; dim[st][i0 + k] = ni; }
;             }
; #pragma unroll
;             for (int st = 0; st < 2; ++st) { const float pr = __shfl_xor(hre[st], 32), pi = __shfl_xor(him[st], 32); if (half != hf) { hre[st] = pr; him[st] = pi; } }
;         }
.LBB0_934:
	s_waitcnt vmcnt(0)
	v_cvt_pk_bf16_f32 v0, v206, v207
	v_cvt_pk_bf16_f32 v1, v208, v209
	v_cvt_pk_bf16_f32 v2, v210, v211
	v_cvt_pk_bf16_f32 v3, v212, v213
	v_add_u32_e32 v4, s30, v179
	v_add_u32_e32 v4, 32, v4
	v_ashrrev_i32_e32 v5, 31, v4
	v_lshlrev_b64 v[4:5], 11, v[4:5]
	v_lshl_add_u64 v[4:5], v[158:159], 0, v[4:5]
	global_load_dwordx4 v[206:209], v[4:5], off
	global_load_dwordx4 v[210:213], v[4:5], off offset:16
	v_add_u32_e32 v226, s30, v180
	v_ashrrev_i32_e32 v227, 31, v226
	v_lshlrev_b64 v[228:229], 9, v[226:227]
	v_or_b32_e32 v228, v228, v96
	v_lshl_add_u64 v[228:229], v[228:229], 2, s[4:5]
	global_load_dwordx4 v[214:217], v[228:229], off
	v_add_u32_e32 v226, 16, v226
	v_ashrrev_i32_e32 v227, 31, v226
	v_lshlrev_b64 v[228:229], 9, v[226:227]
	v_or_b32_e32 v228, v228, v96
	v_lshl_add_u64 v[228:229], v[228:229], 2, s[4:5]
	global_load_dwordx4 v[218:221], v[228:229], off
	global_load_dwordx4 v[222:225], v[160:161], off
	v_mfma_f32_32x32x16_bf16 v[32:47], v[0:3], v[98:101], 0
	v_mfma_f32_32x32x16_bf16 v[80:95], v[0:3], v[114:117], 0
	v_mfma_f32_32x32x16_bf16 v[48:63], v[0:3], v[106:109], 0
	v_mfma_f32_32x32x16_bf16 v[64:79], v[0:3], v[122:125], 0
	s_and_saveexec_b64 s[14:15], s[6:7]
	s_cbranch_execz .LBB0_936
	v_pk_mul_f32 v[0:1], v[152:153], v[162:163] op_sel_hi:[1,0]
	v_pk_mul_f32 v[6:7], v[154:155], v[162:163] op_sel:[0,1]
	v_pk_fma_f32 v[2:3], v[144:145], v[164:165], v[0:1] neg_lo:[0,0,1] neg_hi:[0,0,1]
	v_pk_fma_f32 v[0:1], v[144:145], v[164:165], v[0:1] op_sel_hi:[1,0,1]
	v_pk_fma_f32 v[8:9], v[150:151], v[164:165], v[6:7] op_sel:[0,1,0] neg_lo:[0,0,1] neg_hi:[0,0,1]
	v_mov_b32_e32 v3, v1
	s_nop 0
	v_mov_b32_e32 v0, v32
	v_mov_b32_e32 v1, v80
	v_pk_fma_f32 v[6:7], v[150:151], v[164:165], v[6:7] op_sel:[0,1,0]
	v_pk_add_f32 v[0:1], v[2:3], v[0:1]
	v_mov_b32_e32 v9, v7
	v_mov_b32_e32 v6, v48
	v_mov_b32_e32 v7, v64
	v_pk_mul_f32 v[2:3], v[144:145], v[0:1]
	v_pk_mul_f32 v[4:5], v[152:153], v[0:1]
	v_pk_add_f32 v[6:7], v[8:9], v[6:7]
	v_sub_f32_e32 v2, v2, v3
	v_add_f32_e32 v3, v4, v5
	v_pk_mul_f32 v[8:9], v[150:151], v[6:7]
	v_add_f32_e32 v4, v81, v3
	v_sub_f32_e32 v3, v8, v9
	v_pk_mul_f32 v[10:11], v[154:155], v[6:7]
	v_add_f32_e32 v8, v49, v3
	v_add_f32_e32 v3, v10, v11
	v_add_f32_e32 v10, v65, v3
	v_add_f32_e32 v2, v33, v2
	v_pk_mul_f32 v[12:13], v[144:145], v[4:5] op_sel_hi:[1,0]
	v_pk_mul_f32 v[20:21], v[150:151], v[10:11] op_sel_hi:[1,0]
	v_pk_fma_f32 v[14:15], v[152:153], v[2:3], v[12:13] op_sel_hi:[1,0,1] neg_lo:[0,0,1] neg_hi:[0,0,1]
	v_pk_fma_f32 v[12:13], v[152:153], v[2:3], v[12:13] op_sel_hi:[1,0,1]
	v_pk_fma_f32 v[22:23], v[154:155], v[8:9], v[20:21] op_sel_hi:[1,0,1] neg_lo:[0,0,1] neg_hi:[0,0,1]
	v_pk_fma_f32 v[20:21], v[154:155], v[8:9], v[20:21] op_sel_hi:[1,0,1]
	v_mov_b32_e32 v13, v15
	v_mov_b32_e32 v14, v82
	v_mov_b32_e32 v15, v34
	v_mov_b32_e32 v21, v23
	v_mov_b32_e32 v22, v66
	v_mov_b32_e32 v23, v50
	v_pk_add_f32 v[12:13], v[14:15], v[12:13]
	v_pk_add_f32 v[20:21], v[22:23], v[20:21]
	v_pk_mul_f32 v[14:15], v[144:145], v[12:13] op_sel:[0,1] op_sel_hi:[1,0]
	v_pk_mul_f32 v[16:17], v[156:157], v[12:13]
	v_pk_mul_f32 v[22:23], v[150:151], v[20:21] op_sel:[0,1] op_sel_hi:[1,0]
	v_mov_b32_e32 v50, v35
	v_mov_b32_e32 v15, v22
	v_mov_b32_e32 v17, v23
	v_pk_add_f32 v[14:15], v[14:15], v[16:17] neg_lo:[0,1] neg_hi:[0,1]
	v_pk_mul_f32 v[18:19], v[144:145], v[12:13]
	v_pk_add_f32 v[164:165], v[50:51], v[14:15]
	v_pk_mul_f32 v[14:15], v[150:151], v[20:21]
	v_mov_b32_e32 v16, v19
	v_mov_b32_e32 v17, v15
	v_mov_b32_e32 v19, v14
	v_pk_add_f32 v[14:15], v[16:17], v[18:19]
	v_mov_b32_e32 v66, v83
	v_pk_add_f32 v[162:163], v[66:67], v[14:15]
	v_mov_b32_e32 v64, v7
	v_mov_b32_e32 v65, v10
	v_mov_b32_e32 v66, v20
	v_mov_b32_e32 v67, v163
	v_mov_b32_e32 v80, v1
	v_mov_b32_e32 v81, v4
	v_mov_b32_e32 v82, v12
	v_mov_b32_e32 v83, v162
	v_mov_b32_e32 v32, v0
	v_mov_b32_e32 v33, v2
	v_mov_b32_e32 v34, v13
	v_mov_b32_e32 v35, v164
	v_mov_b32_e32 v48, v6
	v_mov_b32_e32 v49, v8
	v_mov_b32_e32 v50, v21
	v_mov_b32_e32 v51, v165
